# DSA gathers coalesced: 4 neighbouring lanes fetch one key row's 64-byte slice (was 4 different rows); rows parked in the same LDS image, logits MFMA B operand read back from it by ds_read_b128
# speedup vs baseline: 1.0253x; 1.0253x over previous
; #define LAS __attribute__((address_space(3)))
;     ...
;       bf16x8 qa[4];
;       { const u16* qp = prow + qgrow * NP + C_QL + (c16 & 3) * 128 + quad * 8;
; #pragma unroll
;         for (int ks = 0; ks < 4; ++ks) qa[ks] = *(const bf16x8*)(qp + ks * 32); }
;       f32x4 oacc[8];
; #pragma unroll
;       for (int c = 0; c < 8; ++c) oacc[c] = (f32x4){0.f, 0.f, 0.f, 0.f};
;       const unsigned fsw = ((c16 & 3) << 2) | (c16 >> 2);
;       const unsigned wb = (unsigned)(unsigned long long)wbase;
;       unsigned tra[8][2];
;       { const unsigned q4 = c16 >> 2, p4 = c16 & 3;
; #pragma unroll
;         for (int t = 0; t < 2; ++t) { const unsigned fv = (q4 << 2) | ((2 * quad + t) & 3), rowb = wb + (8 * quad + 4 * t + q4) * 256 + 8 * (p4 & 1);
; #pragma unroll
;             for (int c = 0; c < 8; ++c) tra[c][t] = rowb + 16 * ((2 * c + (p4 >> 1)) ^ fv); } }
;       LAS u16* pbT = (LAS u16*)pbuf;
;       float mrun = -1e30f, lsum = 0.f;
;       const int nb = (sm & 8) ? ((kcount + 63) >> 6) : 0;
;       u32x4 w[4][4];
;       auto gl = [&](int b) {
; #pragma unroll
;           for (int jj = 0; jj < 4; ++jj) { const int kx = list[(b * 4 + jj) * 16 + c16] & 4095; const u16* cp = prow + (size_t)kx * NP + C_BC + quad * 8;
; #pragma unroll
;               for (int ks = 0; ks < 4; ++ks) w[jj][ks] = *(const u32x4*)(cp + ks * 32); } };
;       if (nb > 0) gl(0);
.LBB0_926:
	v_lshrrev_b32_e32 v128, 4, v163
	v_and_b32_e32 v127, 15, v174
	v_lshlrev_b32_e32 v18, 3, v128
	v_mov_b32_e32 v109, 0
	s_andn2_b64 vcc, exec, s[0:1]
	v_and_b32_e32 v126, 48, v174
	v_lshlrev_b32_e32 v124, 1, v18
	v_cmp_eq_u32_e64 s[38:39], 0, v127
	v_lshl_add_u32 v129, v128, 2, s56
	v_mov_b32_e32 v108, v109
	v_mov_b32_e32 v107, v109
	v_mov_b32_e32 v106, v109
	v_mov_b32_e32 v113, v109
	v_mov_b32_e32 v112, v109
	v_mov_b32_e32 v111, v109
	v_mov_b32_e32 v110, v109
	v_mov_b32_e32 v93, v109
	v_mov_b32_e32 v92, v109
	v_mov_b32_e32 v91, v109
	v_mov_b32_e32 v90, v109
	v_mov_b32_e32 v85, v109
	v_mov_b32_e32 v84, v109
	v_mov_b32_e32 v83, v109
	v_mov_b32_e32 v82, v109
	v_mov_b32_e32 v89, v109
	v_mov_b32_e32 v88, v109
	v_mov_b32_e32 v87, v109
	v_mov_b32_e32 v86, v109
	v_mov_b32_e32 v97, v109
	v_mov_b32_e32 v96, v109
	v_mov_b32_e32 v95, v109
	v_mov_b32_e32 v94, v109
	v_mov_b32_e32 v105, v109
	v_mov_b32_e32 v104, v109
	v_mov_b32_e32 v103, v109
	v_mov_b32_e32 v102, v109
	v_mov_b32_e32 v101, v109
	v_mov_b32_e32 v100, v109
	v_mov_b32_e32 v99, v109
	v_mov_b32_e32 v98, v109
	v_mov_b32_e32 v118, v109
	s_cbranch_vccnz .LBB0_953
	s_mul_hi_i32 s1, s61, 0x5800
	s_mulk_i32 s61, 0x5800
	v_lshlrev_b32_e32 v0, 7, v127
	s_add_u32 s0, s54, s61
	v_and_b32_e32 v82, 0x180, v0
	s_addc_u32 s1, s55, s1
	v_lshlrev_b32_e32 v0, 1, v82
	v_lshl_add_u64 v[2:3], s[0:1], 0, v[0:1]
	v_lshrrev_b32_e32 v83, 2, v127
	v_lshlrev_b32_e32 v0, 1, v128
	v_and_b32_e32 v84, 12, v174
	v_and_b32_e32 v85, 2, v0
	v_or_b32_e32 v0, v18, v83
	v_lshlrev_b32_e32 v18, 3, v127
	v_or_b32_e32 v86, v85, v84
	v_bfe_u32 v19, v174, 1, 1
	v_and_or_b32 v18, v18, 8, s60
	v_mov_b32_e32 v125, v1
	v_lshl_add_u32 v88, v0, 8, v18
	v_or_b32_e32 v0, v86, v19
	v_or_b32_e32 v89, 2, v19
	v_lshlrev_b32_e32 v95, 1, v127
	v_lshl_add_u64 v[14:15], v[2:3], 0, v[124:125]
	v_lshl_add_u32 v130, v0, 4, v88
	v_bitop3_b32 v0, v85, v89, v84 bitop3:0x36
	v_or_b32_e32 v90, 4, v19
	v_add_u32_e32 v96, s56, v95
	global_load_dwordx4 v[2:5], v[14:15], off offset:3072
	global_load_dwordx4 v[6:9], v[14:15], off offset:3136
	global_load_dwordx4 v[10:13], v[14:15], off offset:3200
	s_nop 0
	global_load_dwordx4 v[14:17], v[14:15], off offset:3264
	v_lshl_add_u32 v131, v0, 4, v88
	v_bitop3_b32 v0, v85, v90, v84 bitop3:0x36
	v_or_b32_e32 v91, 6, v19
	v_bfe_u32 v232, v163, 2, 4
	v_lshl_add_u32 v232, v232, 1, s56
	v_and_b32_e32 v234, 3, v163
	v_lshlrev_b32_e32 v234, 4, v234
	v_mov_b32_e32 v235, 0
	ds_read_u16 v18, v232
	ds_read_u16 v20, v232 offset:32
	v_lshl_add_u32 v132, v0, 4, v88
	v_bitop3_b32 v0, v85, v91, v84 bitop3:0x36
	v_or_b32_e32 v92, 8, v19
	v_lshl_add_u32 v133, v0, 4, v88
	v_bitop3_b32 v0, v85, v92, v84 bitop3:0x36
	v_or_b32_e32 v93, 10, v19
	v_lshl_add_u32 v134, v0, 4, v88
	v_bitop3_b32 v0, v85, v93, v84 bitop3:0x36
	v_or_b32_e32 v94, 12, v19
	v_lshl_add_u32 v135, v0, 4, v88
	v_bitop3_b32 v0, v85, v94, v84 bitop3:0x36
	ds_read_u16 v50, v232 offset:64
	ds_read_u16 v51, v232 offset:96
	s_mov_b32 s1, 0x5040100
	v_lshl_add_u32 v136, v0, 4, v88
	s_waitcnt lgkmcnt(2)
	v_perm_b32 v0, v20, v18, s1
	s_movk_i32 s20, 0xfff
	v_and_b32_e32 v18, 0xfff0fff, v0
	v_bitop3_b32 v0, v0, s20, v207 bitop3:0x80
	v_mul_u32_u24_e32 v0, 0x5800, v0
	v_or_b32_e32 v97, 14, v19
	v_mul_u32_u24_sdwa v34, v18, s33 dst_sel:DWORD dst_unused:UNUSED_PAD src0_sel:WORD_1 src1_sel:DWORD
	v_lshl_add_u64 v[18:19], s[54:55], 0, v[0:1]
	v_lshl_add_u64 v[18:19], v[18:19], 0, v[234:235]
	s_movk_i32 s0, 0x1000
	v_mov_b32_e32 v35, v1
	s_waitcnt lgkmcnt(0)
	v_perm_b32 v0, v51, v50, s1
	v_add_co_u32_e32 v26, vcc, s0, v18
	v_lshl_add_u64 v[34:35], s[54:55], 0, v[34:35]
	v_and_b32_e32 v50, 0xfff0fff, v0
	v_bitop3_b32 v0, v0, s20, v207 bitop3:0x80
	v_addc_co_u32_e32 v27, vcc, 0, v19, vcc
	v_lshl_add_u64 v[34:35], v[34:35], 0, v[234:235]
	v_mul_u32_u24_e32 v0, 0x5800, v0
	v_add_co_u32_e32 v42, vcc, s0, v34
	v_mul_u32_u24_sdwa v66, v50, s33 dst_sel:DWORD dst_unused:UNUSED_PAD src0_sel:WORD_1 src1_sel:DWORD
	v_lshl_add_u64 v[50:51], s[54:55], 0, v[0:1]
	v_addc_co_u32_e32 v43, vcc, 0, v35, vcc
	v_lshl_add_u64 v[50:51], v[50:51], 0, v[234:235]
	v_mov_b32_e32 v67, v1
	v_add_co_u32_e32 v58, vcc, s0, v50
	v_lshl_add_u64 v[66:67], s[54:55], 0, v[66:67]
	s_nop 0
	v_addc_co_u32_e32 v59, vcc, 0, v51, vcc
	v_lshl_add_u64 v[66:67], v[66:67], 0, v[234:235]
	s_mov_b64 s[24:25], 0x1000
	v_add_co_u32_e32 v74, vcc, s0, v66
	v_lshl_add_u64 v[30:31], v[18:19], 0, s[24:25]
	v_lshl_add_u64 v[46:47], v[34:35], 0, s[24:25]
	v_lshl_add_u64 v[62:63], v[50:51], 0, s[24:25]
	v_lshl_add_u64 v[78:79], v[66:67], 0, s[24:25]
	v_addc_co_u32_e32 v75, vcc, 0, v67, vcc
	global_load_dwordx4 v[18:21], v[30:31], off offset:64
	global_load_dwordx4 v[22:25], v[30:31], off offset:128
	s_nop 0
	global_load_dwordx4 v[26:29], v[26:27], off
	s_nop 0
	global_load_dwordx4 v[30:33], v[30:31], off offset:192
	s_nop 0
	global_load_dwordx4 v[34:37], v[46:47], off offset:64
	global_load_dwordx4 v[38:41], v[46:47], off offset:128
	s_nop 0
	global_load_dwordx4 v[42:45], v[42:43], off
	s_nop 0
	global_load_dwordx4 v[46:49], v[46:47], off offset:192
	s_nop 0
	global_load_dwordx4 v[50:53], v[62:63], off offset:64
	global_load_dwordx4 v[54:57], v[62:63], off offset:128
	s_nop 0
	global_load_dwordx4 v[58:61], v[58:59], off
	s_nop 0
	global_load_dwordx4 v[62:65], v[62:63], off offset:192
	s_nop 0
	global_load_dwordx4 v[66:69], v[78:79], off offset:64
	global_load_dwordx4 v[70:73], v[78:79], off offset:128
	s_nop 0
	global_load_dwordx4 v[74:77], v[74:75], off
	s_nop 0
	global_load_dwordx4 v[78:81], v[78:79], off offset:192
	v_lshrrev_b32_e32 v87, 1, v174
	v_bitop3_b32 v0, v85, v97, v84 bitop3:0x36
	v_lshl_add_u32 v137, v0, 4, v88
; #define LAS __attribute__((address_space(3)))
;     ...
;       const unsigned fsw = ((c16 & 3) << 2) | (c16 >> 2);
;       const unsigned wb = (unsigned)(unsigned long long)wbase;
;       unsigned tra[8][2];
;       { const unsigned q4 = c16 >> 2, p4 = c16 & 3;
; #pragma unroll
;         for (int t = 0; t < 2; ++t) { const unsigned fv = (q4 << 2) | ((2 * quad + t) & 3), rowb = wb + (8 * quad + 4 * t + q4) * 256 + 8 * (p4 & 1);
; #pragma unroll
;             for (int c = 0; c < 8; ++c) tra[c][t] = rowb + 16 * ((2 * c + (p4 >> 1)) ^ fv); } }
;       LAS u16* pbT = (LAS u16*)pbuf;
;       float mrun = -1e30f, lsum = 0.f;
;       const int nb = (sm & 8) ? ((kcount + 63) >> 6) : 0;
;       u32x4 w[4][4];
;       auto gl = [&](int b) {
; #pragma unroll
;           for (int jj = 0; jj < 4; ++jj) { const int kx = list[(b * 4 + jj) * 16 + c16] & 4095; const u16* cp = prow + (size_t)kx * NP + C_BC + quad * 8;
; #pragma unroll
;               for (int ks = 0; ks < 4; ++ks) w[jj][ks] = *(const u32x4*)(cp + ks * 32); } };
;       if (nb > 0) gl(0);
;       for (int b = 0; b < nb; ++b) {
;           float lgv[4], rsv[4];
; #pragma unroll
;           for (int jj = 0; jj < 4; ++jj) {
;               const int rho = jj * 16 + c16, slot = b * 64 + rho;
;               f32x4 a = {0.f, 0.f, 0.f, 0.f}; float ss = 0.f;
; #pragma unroll
;               for (int ks = 0; ks < 4; ++ks) {
; #pragma unroll
;                   for (int e = 0; e < 4; ++e) asm("v_dot2_f32_bf16 %0, %1, %1, %0" : "+v"(ss) : "v"(w[jj][ks][e]));
;                   a = __builtin_amdgcn_mfma_f32_16x16x32_bf16(qa[ks], *reinterpret_cast<const bf16x8*>(&w[jj][ks]), a, 0, 0, 0);
;                   *(LAS u32x4*)(wbase + rho * 256 + (((ks * 4 + quad) ^ fsw) << 4)) = w[jj][ks]; }
;               ss += __shfl_xor(ss, 16); ss += __shfl_xor(ss, 32);
;               const float rstd = rsqrtf(ss * (1.f / 128.f) + EPS);
;               const float av = quad == 0 ? a[0] : (quad == 1 ? a[1] : (quad == 2 ? a[2] : a[3]));
;               rsv[jj] = rstd; lgv[jj] = (slot < kcount) ? av * rstd * 0.08838834764831845f : -__builtin_inff();
;           }
	v_add_u32_e32 v0, 0x400, v88
	v_bitop3_b32 v84, v86, v87, 1 bitop3:0x72
	v_lshl_add_u32 v138, v84, 4, v0
	v_bitop3_b32 v84, v86, v89, 1 bitop3:0x36
	v_lshl_add_u32 v139, v84, 4, v0
	v_bitop3_b32 v84, v86, v90, 1 bitop3:0x36
	v_lshl_add_u32 v140, v84, 4, v0
	v_bitop3_b32 v84, v86, v91, 1 bitop3:0x36
	v_lshl_add_u32 v141, v84, 4, v0
	v_bitop3_b32 v84, v86, v92, 1 bitop3:0x36
	v_lshl_add_u32 v142, v84, 4, v0
	v_bitop3_b32 v84, v86, v93, 1 bitop3:0x36
	v_lshl_add_u32 v143, v84, 4, v0
	v_bitop3_b32 v84, v86, v94, 1 bitop3:0x36
	v_lshl_add_u32 v144, v84, 4, v0
	v_bitop3_b32 v84, v86, v97, 1 bitop3:0x36
	v_lshl_add_u32 v145, v84, 4, v0
	v_lshlrev_b32_e32 v0, 2, v127
	v_and_b32_e32 v0, 12, v0
	v_bitop3_b32 v85, v0, v128, v83 bitop3:0x36
	v_lshlrev_b32_e32 v147, 4, v85
	v_or_b32_e32 v85, 4, v128
	v_bitop3_b32 v85, v0, v85, v83 bitop3:0x36
	v_lshlrev_b32_e32 v148, 4, v85
	v_or_b32_e32 v85, 8, v128
	v_bitop3_b32 v85, v0, v85, v83 bitop3:0x36
	v_lshlrev_b32_e32 v149, 4, v85
	v_or_b32_e32 v85, 12, v128
	v_lshlrev_b32_e32 v84, 7, v128
	v_add_u32_e32 v82, s56, v82
	v_lshl_add_u32 v146, v127, 8, s60
	v_bitop3_b32 v0, v0, v85, v83 bitop3:0x36
	s_add_i32 s57, s57, 0x20080
	v_mov_b32_e32 v159, 0
	s_mov_b32 s24, 0
	v_cmp_eq_u32_e64 s[40:41], 2, v128
	v_cmp_eq_u32_e64 s[66:67], 1, v128
	v_cmp_eq_u32_e64 s[68:69], 3, v128
	v_lshlrev_b32_e32 v150, 4, v0
	v_add_u32_e32 v151, 0x1000, v146
	v_add_u32_e32 v152, 0x2000, v146
	v_add_u32_e32 v153, 0x3000, v146
	v_bfe_u32 v236, v163, 2, 4
	v_and_b32_e32 v237, 3, v163
	v_lshlrev_b32_e32 v249, 4, v237
	v_and_b32_e32 v238, 3, v236
	v_lshrrev_b32_e32 v239, 2, v236
	v_lshl_or_b32 v238, v238, 2, v239
	v_xor_b32_e32 v237, v237, v238
	v_lshl_add_u32 v239, v236, 8, s60
	v_lshl_add_u32 v244, v237, 4, v239
	v_xor_b32_e32 v240, 4, v237
	v_lshl_add_u32 v245, v240, 4, v239
	v_xor_b32_e32 v240, 8, v237
	v_lshl_add_u32 v246, v240, 4, v239
	v_xor_b32_e32 v240, 12, v237
	v_lshl_add_u32 v247, v240, 4, v239
	v_xor_b32_e32 v248, 32, v206
	v_lshlrev_b32_e32 v248, 2, v248
	v_bfe_u32 v154, v163, 2, 4
	v_lshl_add_u32 v154, v154, 1, s57
	v_mov_b32_e32 v160, 0xf149f2ca
	v_add_u32_e32 v155, v96, v84
	v_add_u32_e32 v156, v82, v126
	v_mov_b32_e32 v157, v127
	v_mov_b32_e32 v98, 0
	v_mov_b32_e32 v99, v159
	v_mov_b32_e32 v100, v159
	v_mov_b32_e32 v101, v159
	v_mov_b32_e32 v102, 0
	v_mov_b32_e32 v103, v159
	v_mov_b32_e32 v104, v159
	v_mov_b32_e32 v105, v159
	v_mov_b32_e32 v94, 0
	v_mov_b32_e32 v95, v159
	v_mov_b32_e32 v96, v159
	v_mov_b32_e32 v97, v159
	v_mov_b32_e32 v86, 0
	v_mov_b32_e32 v87, v159
	v_mov_b32_e32 v88, v159
	v_mov_b32_e32 v89, v159
	v_mov_b32_e32 v82, 0
	v_mov_b32_e32 v83, v159
	v_mov_b32_e32 v84, v159
	v_mov_b32_e32 v85, v159
	v_mov_b32_e32 v90, 0
	v_mov_b32_e32 v91, v159
	v_mov_b32_e32 v92, v159
	v_mov_b32_e32 v93, v159
	v_mov_b32_e32 v110, 0
	v_mov_b32_e32 v111, v159
	v_mov_b32_e32 v112, v159
	v_mov_b32_e32 v113, v159
	v_mov_b32_e32 v106, 0
	v_mov_b32_e32 v107, v159
	v_mov_b32_e32 v108, v159
	v_mov_b32_e32 v109, v159
.LBB0_928:
	s_add_i32 s0, s24, 1
	s_cmp_ge_i32 s0, s23
	s_cbranch_scc0 .Ldsa_steady
	s_waitcnt vmcnt(12)
	ds_write_b128 v244, v[26:29]
	ds_write_b128 v245, v[18:21]
	ds_write_b128 v246, v[22:25]
	ds_write_b128 v247, v[30:33]
	v_add_u32_e32 v0, v146, v147
	ds_read_b128 v[232:235], v0
	v_add_u32_e32 v0, v146, v148
	ds_read_b128 v[236:239], v0
	v_add_u32_e32 v0, v146, v149
	ds_read_b128 v[240:243], v0
	v_add_u32_e32 v0, v146, v150
	v_mov_b32_e32 v118, 0
	s_waitcnt lgkmcnt(2)
	v_dot2_f32_bf16 v118, v232, v232, v118
	v_dot2_f32_bf16 v118, v233, v233, v118
	v_dot2_f32_bf16 v118, v234, v234, v118
	v_dot2_f32_bf16 v118, v235, v235, v118
	v_mfma_f32_16x16x32_bf16 v[114:117], v[2:5], v[232:235], 0
	ds_read_b128 v[232:235], v0
	s_waitcnt lgkmcnt(2)
	v_dot2_f32_bf16 v118, v236, v236, v118
	v_dot2_f32_bf16 v118, v237, v237, v118
	v_dot2_f32_bf16 v118, v238, v238, v118
	v_dot2_f32_bf16 v118, v239, v239, v118
	v_mfma_f32_16x16x32_bf16 v[114:117], v[6:9], v[236:239], v[114:117]
	s_waitcnt lgkmcnt(1)
	v_dot2_f32_bf16 v118, v240, v240, v118
	v_dot2_f32_bf16 v118, v241, v241, v118
	v_dot2_f32_bf16 v118, v242, v242, v118
	v_dot2_f32_bf16 v118, v243, v243, v118
	v_mfma_f32_16x16x32_bf16 v[114:117], v[10:13], v[240:243], v[114:117]
	s_waitcnt lgkmcnt(0)
	v_dot2_f32_bf16 v118, v232, v232, v118
	v_dot2_f32_bf16 v118, v233, v233, v118
	v_dot2_f32_bf16 v118, v234, v234, v118
	v_dot2_f32_bf16 v118, v235, v235, v118
	v_mfma_f32_16x16x32_bf16 v[114:117], v[14:17], v[232:235], v[114:117]
	s_nop 2
	v_mov_b32_e32 v119, v118
	s_nop 1
	v_permlane16_swap_b32_e32 v118, v119
	v_add_f32_e32 v161, v118, v119
	ds_bpermute_b32 v172, v248, v161
	v_cndmask_b32_e64 v114, v114, v115, s[66:67]
	v_cndmask_b32_e64 v114, v114, v116, s[40:41]
	v_cndmask_b32_e64 v114, v114, v117, s[68:69]
	s_waitcnt vmcnt(8)
	ds_write_b128 v244, v[42:45] offset:4096
	ds_write_b128 v245, v[34:37] offset:4096
	ds_write_b128 v246, v[38:41] offset:4096
	ds_write_b128 v247, v[46:49] offset:4096
	v_add_u32_e32 v0, v146, v147
	ds_read_b128 v[232:235], v0 offset:4096
	v_add_u32_e32 v0, v146, v148
	ds_read_b128 v[236:239], v0 offset:4096
	v_add_u32_e32 v0, v146, v149
	ds_read_b128 v[240:243], v0 offset:4096
	v_add_u32_e32 v0, v146, v150
	v_mov_b32_e32 v115, 0
	s_waitcnt lgkmcnt(2)
	v_dot2_f32_bf16 v115, v232, v232, v115
	v_dot2_f32_bf16 v115, v233, v233, v115
	v_dot2_f32_bf16 v115, v234, v234, v115
	v_dot2_f32_bf16 v115, v235, v235, v115
	v_mfma_f32_16x16x32_bf16 v[116:119], v[2:5], v[232:235], 0
	ds_read_b128 v[232:235], v0 offset:4096
	s_waitcnt lgkmcnt(2)
	v_dot2_f32_bf16 v115, v236, v236, v115
	v_dot2_f32_bf16 v115, v237, v237, v115
	v_dot2_f32_bf16 v115, v238, v238, v115
	v_dot2_f32_bf16 v115, v239, v239, v115
	v_mfma_f32_16x16x32_bf16 v[116:119], v[6:9], v[236:239], v[116:119]
	s_waitcnt lgkmcnt(1)
; #define LAS __attribute__((address_space(3)))
;     ...
;           for (int jj = 0; jj < 4; ++jj) {
;               const int rho = jj * 16 + c16, slot = b * 64 + rho;
;               f32x4 a = {0.f, 0.f, 0.f, 0.f}; float ss = 0.f;
; #pragma unroll
;               for (int ks = 0; ks < 4; ++ks) {
; #pragma unroll
;                   for (int e = 0; e < 4; ++e) asm("v_dot2_f32_bf16 %0, %1, %1, %0" : "+v"(ss) : "v"(w[jj][ks][e]));
;                   a = __builtin_amdgcn_mfma_f32_16x16x32_bf16(qa[ks], *reinterpret_cast<const bf16x8*>(&w[jj][ks]), a, 0, 0, 0);
;                   *(LAS u32x4*)(wbase + rho * 256 + (((ks * 4 + quad) ^ fsw) << 4)) = w[jj][ks]; }
;               ss += __shfl_xor(ss, 16); ss += __shfl_xor(ss, 32);
;               const float rstd = rsqrtf(ss * (1.f / 128.f) + EPS);
;               const float av = quad == 0 ? a[0] : (quad == 1 ? a[1] : (quad == 2 ? a[2] : a[3]));
;               rsv[jj] = rstd; lgv[jj] = (slot < kcount) ? av * rstd * 0.08838834764831845f : -__builtin_inff();
;           }
	v_dot2_f32_bf16 v115, v240, v240, v115
	v_dot2_f32_bf16 v115, v241, v241, v115
	v_dot2_f32_bf16 v115, v242, v242, v115
	v_dot2_f32_bf16 v115, v243, v243, v115
	v_mfma_f32_16x16x32_bf16 v[116:119], v[10:13], v[240:243], v[116:119]
	s_waitcnt lgkmcnt(0)
	v_dot2_f32_bf16 v115, v232, v232, v115
	v_dot2_f32_bf16 v115, v233, v233, v115
	v_dot2_f32_bf16 v115, v234, v234, v115
	v_dot2_f32_bf16 v115, v235, v235, v115
	v_mfma_f32_16x16x32_bf16 v[116:119], v[14:17], v[232:235], v[116:119]
	s_nop 2
	v_mov_b32_e32 v120, v115
	s_nop 1
	v_permlane16_swap_b32_e32 v115, v120
	v_add_f32_e32 v115, v115, v120
	ds_bpermute_b32 v173, v248, v115
	v_cndmask_b32_e64 v116, v116, v117, s[66:67]
	v_cndmask_b32_e64 v116, v116, v118, s[40:41]
	v_cndmask_b32_e64 v116, v116, v119, s[68:69]
	s_waitcnt vmcnt(4)
	ds_write_b128 v244, v[58:61] offset:8192
	ds_write_b128 v245, v[50:53] offset:8192
	ds_write_b128 v246, v[54:57] offset:8192
	ds_write_b128 v247, v[62:65] offset:8192
	v_add_u32_e32 v0, v146, v147
	ds_read_b128 v[232:235], v0 offset:8192
	v_add_u32_e32 v0, v146, v148
	ds_read_b128 v[236:239], v0 offset:8192
	v_add_u32_e32 v0, v146, v149
	ds_read_b128 v[240:243], v0 offset:8192
	v_add_u32_e32 v0, v146, v150
	v_mov_b32_e32 v117, 0
	s_waitcnt lgkmcnt(2)
	v_dot2_f32_bf16 v117, v232, v232, v117
	v_dot2_f32_bf16 v117, v233, v233, v117
	v_dot2_f32_bf16 v117, v234, v234, v117
	v_dot2_f32_bf16 v117, v235, v235, v117
	v_mfma_f32_16x16x32_bf16 v[118:121], v[2:5], v[232:235], 0
	ds_read_b128 v[232:235], v0 offset:8192
	s_waitcnt lgkmcnt(2)
	v_dot2_f32_bf16 v117, v236, v236, v117
	v_dot2_f32_bf16 v117, v237, v237, v117
	v_dot2_f32_bf16 v117, v238, v238, v117
	v_dot2_f32_bf16 v117, v239, v239, v117
	v_mfma_f32_16x16x32_bf16 v[118:121], v[6:9], v[236:239], v[118:121]
	s_waitcnt lgkmcnt(1)
	v_dot2_f32_bf16 v117, v240, v240, v117
	v_dot2_f32_bf16 v117, v241, v241, v117
	v_dot2_f32_bf16 v117, v242, v242, v117
	v_dot2_f32_bf16 v117, v243, v243, v117
	v_mfma_f32_16x16x32_bf16 v[118:121], v[10:13], v[240:243], v[118:121]
	s_waitcnt lgkmcnt(0)
	v_dot2_f32_bf16 v117, v232, v232, v117
	v_dot2_f32_bf16 v117, v233, v233, v117
	v_dot2_f32_bf16 v117, v234, v234, v117
	v_dot2_f32_bf16 v117, v235, v235, v117
	v_mfma_f32_16x16x32_bf16 v[118:121], v[14:17], v[232:235], v[118:121]
	s_nop 2
	v_mov_b32_e32 v123, v117
	s_nop 1
	v_permlane16_swap_b32_e32 v117, v123
	v_add_f32_e32 v117, v117, v123
	ds_bpermute_b32 v174, v248, v117
	v_cndmask_b32_e64 v118, v118, v119, s[66:67]
	v_cndmask_b32_e64 v118, v118, v120, s[40:41]
	v_cndmask_b32_e64 v118, v118, v121, s[68:69]
	s_waitcnt vmcnt(0)
	ds_write_b128 v244, v[74:77] offset:12288
	ds_write_b128 v245, v[66:69] offset:12288
	ds_write_b128 v246, v[70:73] offset:12288
	ds_write_b128 v247, v[78:81] offset:12288
	v_add_u32_e32 v0, v146, v147
	ds_read_b128 v[232:235], v0 offset:12288
	v_add_u32_e32 v0, v146, v148
	ds_read_b128 v[236:239], v0 offset:12288
	v_add_u32_e32 v0, v146, v149
	ds_read_b128 v[240:243], v0 offset:12288
	v_add_u32_e32 v0, v146, v150
	v_mov_b32_e32 v119, 0
	s_waitcnt lgkmcnt(2)
	v_dot2_f32_bf16 v119, v232, v232, v119
	v_dot2_f32_bf16 v119, v233, v233, v119
	v_dot2_f32_bf16 v119, v234, v234, v119
	v_dot2_f32_bf16 v119, v235, v235, v119
	v_mfma_f32_16x16x32_bf16 v[176:179], v[2:5], v[232:235], 0
	ds_read_b128 v[232:235], v0 offset:12288
	s_waitcnt lgkmcnt(2)
	v_dot2_f32_bf16 v119, v236, v236, v119
	v_dot2_f32_bf16 v119, v237, v237, v119
	v_dot2_f32_bf16 v119, v238, v238, v119
	v_dot2_f32_bf16 v119, v239, v239, v119
	v_mfma_f32_16x16x32_bf16 v[176:179], v[6:9], v[236:239], v[176:179]
	s_waitcnt lgkmcnt(1)
	v_dot2_f32_bf16 v119, v240, v240, v119
	v_dot2_f32_bf16 v119, v241, v241, v119
	v_dot2_f32_bf16 v119, v242, v242, v119
	v_dot2_f32_bf16 v119, v243, v243, v119
	v_mfma_f32_16x16x32_bf16 v[176:179], v[10:13], v[240:243], v[176:179]
	s_waitcnt lgkmcnt(0)
	v_dot2_f32_bf16 v119, v232, v232, v119
	v_dot2_f32_bf16 v119, v233, v233, v119
	v_dot2_f32_bf16 v119, v234, v234, v119
	v_dot2_f32_bf16 v119, v235, v235, v119
	v_mfma_f32_16x16x32_bf16 v[120:123], v[14:17], v[232:235], v[176:179]
	s_nop 2
	v_mov_b32_e32 v0, v119
	s_nop 1
	v_permlane16_swap_b32_e32 v119, v0
	v_add_f32_e32 v119, v119, v0
	ds_bpermute_b32 v175, v248, v119
	v_cndmask_b32_e64 v120, v120, v121, s[66:67]
	v_cndmask_b32_e64 v120, v120, v122, s[40:41]
	v_cndmask_b32_e64 v120, v120, v123, s[68:69]
	s_add_i32 s24, s24, 1
; #define LAS __attribute__((address_space(3)))
; __device__ __forceinline__ u16 f2bf(float f) { return (u16)(cvtpk(f, 0.f) & 0xffffu); }
;     ...
;               ss += __shfl_xor(ss, 16); ss += __shfl_xor(ss, 32);
;               const float rstd = rsqrtf(ss * (1.f / 128.f) + EPS);
;               const float av = quad == 0 ? a[0] : (quad == 1 ? a[1] : (quad == 2 ? a[2] : a[3]));
;               rsv[jj] = rstd; lgv[jj] = (slot < kcount) ? av * rstd * 0.08838834764831845f : -__builtin_inff();
;           }
;           if (b + 1 < nb) gl(b + 1);
;           float mx = fmaxf(fmaxf(lgv[0], lgv[1]), fmaxf(lgv[2], lgv[3]));
; #pragma unroll
;           for (int o = 1; o < 16; o <<= 1) mx = fmaxf(mx, __shfl_xor(mx, o));
;           const float mnew = fmaxf(mrun, mx), alpha = __expf(mrun - mnew); mrun = mnew;
;           float ps = 0.f;
; #pragma unroll
;           for (int jj = 0; jj < 4; ++jj) { const float pe = __expf(lgv[jj] - mnew); ps += pe; pbT[quad * 64 + jj * 16 + c16] = f2bf(pe * rsv[jj]); }
;           lsum = lsum * alpha + ps;
;           if (c16 == 0) alf[quad] = alpha;
;           const f32x4 al4 = *(const LAS f32x4*)alf;
; #pragma unroll
;           for (int c = 0; c < 8; ++c) oacc[c] *= al4;
; #pragma unroll
;           for (int ks = 0; ks < 2; ++ks) {
;               const bf16x8 pf = *(const LAS bf16x8*)(pbT + (c16 & 3) * 64 + ks * 32 + quad * 8);
;               u16x4 t0[8], t1[8];
;     ...
;               if (ks == 0) { TRR8(t0, 0, 0); TRR8(t1, 1, 0); } else { TRR8(t0, 0, 8192); TRR8(t1, 1, 8192); }
;     ...
; #pragma unroll
;               for (int c = 0; c < 8; ++c) {
;                   const bf16x8 bf = {(short)t0[c][0], (short)t0[c][1], (short)t0[c][2], (short)t0[c][3], (short)t1[c][0], (short)t1[c][1], (short)t1[c][2], (short)t1[c][3]};
;                   oacc[c] = __builtin_amdgcn_mfma_f32_16x16x32_bf16(pf, bf, oacc[c], 0, 0, 0);
;               }
;           }
.LBB0_946:
	s_waitcnt lgkmcnt(0)
	v_add_f32_e32 v119, v119, v175
	v_add_f32_e32 v117, v117, v174
	v_add_f32_e32 v115, v115, v173
	v_add_f32_e32 v0, v161, v172
	v_fmamk_f32 v119, v119, 0x3c000000, v199
	v_fmamk_f32 v117, v117, 0x3c000000, v199
	v_fmamk_f32 v115, v115, 0x3c000000, v199
	v_fmamk_f32 v0, v0, 0x3c000000, v199
	v_rsq_f32_e32 v122, v119
	v_rsq_f32_e32 v123, v117
	v_rsq_f32_e32 v125, v115
	v_rsq_f32_e32 v161, v0
	v_add_u32_e32 v0, 48, v157
	v_add_u32_e32 v115, 32, v157
	v_mul_f32_e32 v119, v122, v120
	v_cmp_gt_i32_e32 vcc, s22, v0
	v_mul_f32_e32 v117, v123, v118
	v_mul_f32_e32 v119, 0x3db504f3, v119
	v_cndmask_b32_e32 v121, v208, v119, vcc
	v_cmp_gt_i32_e32 vcc, s22, v115
	v_mul_f32_e32 v117, 0x3db504f3, v117
	v_add_u32_e32 v0, 16, v157
	v_cndmask_b32_e32 v120, v208, v117, vcc
	v_mul_f32_e32 v119, v125, v116
	v_cmp_gt_i32_e32 vcc, s22, v0
	v_mul_f32_e32 v119, 0x3db504f3, v119
	v_mul_f32_e32 v0, v161, v114
	v_cndmask_b32_e32 v119, v208, v119, vcc
	v_cmp_gt_i32_e32 vcc, s22, v157
	v_mul_f32_e32 v0, 0x3db504f3, v0
	s_nop 0
	v_cndmask_b32_e32 v118, v208, v0, vcc
	v_max_f32_e32 v0, v120, v121
	v_max3_f32 v114, v118, v119, v0
	s_nop 1
	v_max_f32_dpp v115, v114, v114 quad_perm:[1,0,3,2] row_mask:0xf bank_mask:0xf
	s_nop 1
	v_max_f32_dpp v116, v115, v115 quad_perm:[2,3,0,1] row_mask:0xf bank_mask:0xf
	s_nop 1
	v_max_f32_dpp v117, v116, v116 row_ror:4 row_mask:0xf bank_mask:0xf
	s_nop 1
	v_max_f32_dpp v172, v117, v117 row_ror:8 row_mask:0xf bank_mask:0xf
	v_max3_f32 v117, v160, v117, v172
	v_sub_f32_e32 v118, v118, v117
	v_sub_f32_e32 v119, v119, v117
	v_sub_f32_e32 v120, v120, v117
	v_sub_f32_e32 v121, v121, v117
	v_mul_f32_e32 v118, 0x3fb8aa3b, v118
	v_mul_f32_e32 v119, 0x3fb8aa3b, v119
	v_mul_f32_e32 v120, 0x3fb8aa3b, v120
	v_mul_f32_e32 v121, 0x3fb8aa3b, v121
	v_exp_f32_e32 v118, v118
	v_exp_f32_e32 v119, v119
	v_exp_f32_e32 v120, v120
	v_exp_f32_e32 v121, v121
	v_sub_f32_e32 v160, v160, v117
	v_mul_f32_e32 v161, v161, v118
	v_mul_f32_e32 v125, v125, v119
	v_mul_f32_e32 v123, v123, v120
	v_mul_f32_e32 v122, v122, v121
	v_mul_f32_e32 v160, 0x3fb8aa3b, v160
	v_cvt_pk_bf16_f32 v161, v161, v1
	ds_write_b16 v155, v161 offset:1024
	v_cvt_pk_bf16_f32 v125, v125, v1
	ds_write_b16 v155, v125 offset:1056
	v_cvt_pk_bf16_f32 v123, v123, v1
	ds_write_b16 v155, v123 offset:1088
	v_cvt_pk_bf16_f32 v122, v122, v1
	ds_write_b16 v155, v122 offset:1120
	v_exp_f32_e32 v122, v160
	s_and_saveexec_b64 s[0:1], s[38:39]
	ds_write_b32 v129, v122 offset:640
	s_or_b64 exec, exec, s[0:1]
	v_add_f32_e32 v118, 0, v118
	v_add_f32_e32 v118, v119, v118
	v_add_f32_e32 v118, v120, v118
	v_add_f32_e32 v118, v121, v118
	v_mov_b32_e32 v119, s56
	v_fmac_f32_e32 v118, v159, v122
	ds_read_b128 v[120:123], v119 offset:640
	v_add_u32_e32 v154, 0x80, v154
	v_add_u32_e32 v157, 64, v157
	s_cmp_eq_u32 s23, s24
	s_waitcnt lgkmcnt(0)
	v_mul_f32_e32 v174, v92, v122
	v_mul_f32_e32 v175, v93, v123
	v_mul_f32_e32 v172, v90, v120
	v_mul_f32_e32 v173, v91, v121
	v_mul_f32_e32 v92, v96, v122
	v_mul_f32_e32 v93, v97, v123
	v_mul_f32_e32 v90, v94, v120
	v_mul_f32_e32 v91, v95, v121
	ds_read_b128 v[94:97], v156 offset:1024
	ds_read_b64_tr_b16 v[216:217], v130 offset:0
	ds_read_b64_tr_b16 v[218:219], v138 offset:0
	ds_read_b64_tr_b16 v[212:213], v131 offset:0
	ds_read_b64_tr_b16 v[214:215], v139 offset:0
	ds_read_b64_tr_b16 v[194:195], v132 offset:0
	ds_read_b64_tr_b16 v[196:197], v140 offset:0
	ds_read_b64_tr_b16 v[190:191], v133 offset:0
	ds_read_b64_tr_b16 v[192:193], v141 offset:0
	ds_read_b64_tr_b16 v[186:187], v134 offset:0
	ds_read_b64_tr_b16 v[188:189], v142 offset:0
	v_mul_f32_e32 v106, v106, v120
	v_mul_f32_e32 v107, v107, v121
	v_mul_f32_e32 v110, v110, v120
	v_mul_f32_e32 v111, v111, v121
	v_mul_f32_e32 v176, v82, v120
	v_mul_f32_e32 v177, v83, v121
	v_mul_f32_e32 v182, v86, v120
	v_mul_f32_e32 v183, v87, v121
	v_mul_f32_e32 v86, v102, v120
	v_mul_f32_e32 v87, v103, v121
	v_mul_f32_e32 v82, v98, v120
	v_mul_f32_e32 v83, v99, v121
	v_mul_f32_e32 v108, v108, v122
	v_mul_f32_e32 v109, v109, v123
	v_mul_f32_e32 v112, v112, v122
	v_mul_f32_e32 v113, v113, v123
	v_mul_f32_e32 v178, v84, v122
	v_mul_f32_e32 v179, v85, v123
	v_mul_f32_e32 v184, v88, v122
	v_mul_f32_e32 v185, v89, v123
	v_mul_f32_e32 v88, v104, v122
	v_mul_f32_e32 v89, v105, v123
	v_mul_f32_e32 v84, v100, v122
	v_mul_f32_e32 v85, v101, v123
	ds_read_b64_tr_b16 v[120:121], v135 offset:0
	ds_read_b64_tr_b16 v[122:123], v143 offset:0
	ds_read_b64_tr_b16 v[102:103], v136 offset:0
	ds_read_b64_tr_b16 v[104:105], v144 offset:0
	s_waitcnt lgkmcnt(12)
	v_mfma_f32_16x16x32_bf16 v[106:109], v[94:97], v[216:219], v[106:109]
	ds_read_b64_tr_b16 v[98:99], v137 offset:0
	ds_read_b64_tr_b16 v[100:101], v145 offset:0
	s_waitcnt lgkmcnt(12)
	v_mfma_f32_16x16x32_bf16 v[110:113], v[94:97], v[212:215], v[110:113]
	s_waitcnt lgkmcnt(10)
	v_mfma_f32_16x16x32_bf16 v[172:175], v[94:97], v[194:197], v[172:175]
	s_waitcnt lgkmcnt(8)
	v_mfma_f32_16x16x32_bf16 v[176:179], v[94:97], v[190:193], v[176:179]
	s_waitcnt lgkmcnt(6)
	v_mfma_f32_16x16x32_bf16 v[182:185], v[94:97], v[186:189], v[182:185]
	s_waitcnt lgkmcnt(4)
	v_mfma_f32_16x16x32_bf16 v[120:123], v[94:97], v[120:123], v[90:93]
	s_waitcnt lgkmcnt(2)
	v_mfma_f32_16x16x32_bf16 v[102:105], v[94:97], v[102:105], v[86:89]
	s_waitcnt lgkmcnt(0)
	v_mfma_f32_16x16x32_bf16 v[98:101], v[94:97], v[98:101], v[82:85]
	ds_read_b128 v[220:223], v156 offset:1088
	ds_read_b64_tr_b16 v[212:213], v130 offset:8192
	ds_read_b64_tr_b16 v[214:215], v138 offset:8192
	ds_read_b64_tr_b16 v[194:195], v131 offset:8192
	ds_read_b64_tr_b16 v[196:197], v139 offset:8192
	ds_read_b64_tr_b16 v[90:91], v132 offset:8192
	ds_read_b64_tr_b16 v[92:93], v140 offset:8192
	ds_read_b64_tr_b16 v[82:83], v133 offset:8192
	ds_read_b64_tr_b16 v[84:85], v141 offset:8192
	ds_read_b64_tr_b16 v[86:87], v134 offset:8192
	ds_read_b64_tr_b16 v[88:89], v142 offset:8192
	ds_read_b64_tr_b16 v[94:95], v135 offset:8192
	ds_read_b64_tr_b16 v[96:97], v143 offset:8192
	ds_read_b64_tr_b16 v[190:191], v136 offset:8192
	ds_read_b64_tr_b16 v[192:193], v144 offset:8192
	s_waitcnt lgkmcnt(12)
	v_mfma_f32_16x16x32_bf16 v[106:109], v[220:223], v[212:215], v[106:109]
	ds_read_b64_tr_b16 v[186:187], v137 offset:8192
	ds_read_b64_tr_b16 v[188:189], v145 offset:8192
	s_waitcnt lgkmcnt(12)
	v_mfma_f32_16x16x32_bf16 v[110:113], v[220:223], v[194:197], v[110:113]
	s_waitcnt lgkmcnt(10)
	v_mfma_f32_16x16x32_bf16 v[90:93], v[220:223], v[90:93], v[172:175]
	s_waitcnt lgkmcnt(8)
	v_mfma_f32_16x16x32_bf16 v[82:85], v[220:223], v[82:85], v[176:179]
	s_waitcnt lgkmcnt(6)
	v_mfma_f32_16x16x32_bf16 v[86:89], v[220:223], v[86:89], v[182:185]
	s_waitcnt lgkmcnt(4)
	v_mfma_f32_16x16x32_bf16 v[94:97], v[220:223], v[94:97], v[120:123]
	s_waitcnt lgkmcnt(2)
	v_mfma_f32_16x16x32_bf16 v[102:105], v[220:223], v[190:193], v[102:105]
	s_waitcnt lgkmcnt(0)
	v_mfma_f32_16x16x32_bf16 v[98:101], v[220:223], v[186:189], v[98:101]
	s_cbranch_scc1 .LBB0_952
	v_mov_b32_e32 v159, v118
	v_mov_b32_e32 v160, v117
	s_branch .LBB0_928
; #define LAS __attribute__((address_space(3)))
;     ...
;       auto gl = [&](int b) {
; #pragma unroll
;           for (int jj = 0; jj < 4; ++jj) { const int kx = list[(b * 4 + jj) * 16 + c16] & 4095; const u16* cp = prow + (size_t)kx * NP + C_BC + quad * 8;
; #pragma unroll
;               for (int ks = 0; ks < 4; ++ks) w[jj][ks] = *(const u32x4*)(cp + ks * 32); } };
;       if (nb > 0) gl(0);
;       for (int b = 0; b < nb; ++b) {
;           float lgv[4], rsv[4];
; #pragma unroll
;           for (int jj = 0; jj < 4; ++jj) {
;               const int rho = jj * 16 + c16, slot = b * 64 + rho;
;               f32x4 a = {0.f, 0.f, 0.f, 0.f}; float ss = 0.f;
; #pragma unroll
;               for (int ks = 0; ks < 4; ++ks) {
; #pragma unroll
;                   for (int e = 0; e < 4; ++e) asm("v_dot2_f32_bf16 %0, %1, %1, %0" : "+v"(ss) : "v"(w[jj][ks][e]));
;                   a = __builtin_amdgcn_mfma_f32_16x16x32_bf16(qa[ks], *reinterpret_cast<const bf16x8*>(&w[jj][ks]), a, 0, 0, 0);
;                   *(LAS u32x4*)(wbase + rho * 256 + (((ks * 4 + quad) ^ fsw) << 4)) = w[jj][ks]; }
;               ss += __shfl_xor(ss, 16); ss += __shfl_xor(ss, 32);
;               const float rstd = rsqrtf(ss * (1.f / 128.f) + EPS);
;               const float av = quad == 0 ? a[0] : (quad == 1 ? a[1] : (quad == 2 ? a[2] : a[3]));
;               rsv[jj] = rstd; lgv[jj] = (slot < kcount) ? av * rstd * 0.08838834764831845f : -__builtin_inff();
;           }
;           if (b + 1 < nb) gl(b + 1);
.Ldsa_steady:
	ds_read_u16 v232, v154
	ds_read_u16 v234, v154 offset:32
	ds_read_u16 v236, v154 offset:64
	ds_read_u16 v238, v154 offset:96
	v_mov_b32_e32 v240, v249
	v_mov_b32_e32 v241, 0
	v_mov_b32_e32 v233, 0
	v_mov_b32_e32 v235, 0
	v_mov_b32_e32 v237, 0
	v_mov_b32_e32 v239, 0
	s_mov_b64 s[0:1], 0x1000
	v_lshl_add_u64 v[242:243], s[54:55], 0, v[240:241]
	v_lshl_add_u64 v[242:243], v[242:243], 0, s[0:1]
	s_waitcnt lgkmcnt(0)
	v_and_b32_e32 v232, 0xfff, v232
	v_mul_u32_u24_e32 v232, 0x5800, v232
	v_lshl_add_u64 v[224:225], v[232:233], 0, v[242:243]
	v_and_b32_e32 v234, 0xfff, v234
	v_mul_u32_u24_e32 v234, 0x5800, v234
	v_lshl_add_u64 v[226:227], v[234:235], 0, v[242:243]
	v_and_b32_e32 v236, 0xfff, v236
	v_mul_u32_u24_e32 v236, 0x5800, v236
	v_lshl_add_u64 v[228:229], v[236:237], 0, v[242:243]
	v_and_b32_e32 v238, 0xfff, v238
	v_mul_u32_u24_e32 v238, 0x5800, v238
	v_lshl_add_u64 v[230:231], v[238:239], 0, v[242:243]
	s_waitcnt vmcnt(12)
	ds_write_b128 v244, v[26:29]
	ds_write_b128 v245, v[18:21]
	ds_write_b128 v246, v[22:25]
	ds_write_b128 v247, v[30:33]
	global_load_dwordx4 v[18:21], v[224:225], off offset:64
	global_load_dwordx4 v[22:25], v[224:225], off offset:128
	global_load_dwordx4 v[26:29], v[224:225], off
	global_load_dwordx4 v[30:33], v[224:225], off offset:192
	v_add_u32_e32 v0, v146, v147
	ds_read_b128 v[232:235], v0
	v_add_u32_e32 v0, v146, v148
	ds_read_b128 v[236:239], v0
	v_add_u32_e32 v0, v146, v149
	ds_read_b128 v[240:243], v0
	v_add_u32_e32 v0, v146, v150
	v_mov_b32_e32 v118, 0
	s_waitcnt lgkmcnt(2)
	v_dot2_f32_bf16 v118, v232, v232, v118
	v_dot2_f32_bf16 v118, v233, v233, v118
	v_dot2_f32_bf16 v118, v234, v234, v118
	v_dot2_f32_bf16 v118, v235, v235, v118
	v_mfma_f32_16x16x32_bf16 v[114:117], v[2:5], v[232:235], 0
	ds_read_b128 v[232:235], v0
	s_waitcnt lgkmcnt(2)
	v_dot2_f32_bf16 v118, v236, v236, v118
	v_dot2_f32_bf16 v118, v237, v237, v118
	v_dot2_f32_bf16 v118, v238, v238, v118
	v_dot2_f32_bf16 v118, v239, v239, v118
	v_mfma_f32_16x16x32_bf16 v[114:117], v[6:9], v[236:239], v[114:117]
	s_waitcnt lgkmcnt(1)
	v_dot2_f32_bf16 v118, v240, v240, v118
	v_dot2_f32_bf16 v118, v241, v241, v118
	v_dot2_f32_bf16 v118, v242, v242, v118
	v_dot2_f32_bf16 v118, v243, v243, v118
	v_mfma_f32_16x16x32_bf16 v[114:117], v[10:13], v[240:243], v[114:117]
	s_waitcnt lgkmcnt(0)
	v_dot2_f32_bf16 v118, v232, v232, v118
	v_dot2_f32_bf16 v118, v233, v233, v118
	v_dot2_f32_bf16 v118, v234, v234, v118
	v_dot2_f32_bf16 v118, v235, v235, v118
	v_mfma_f32_16x16x32_bf16 v[114:117], v[14:17], v[232:235], v[114:117]
	s_nop 2
	v_mov_b32_e32 v119, v118
	s_nop 1
	v_permlane16_swap_b32_e32 v118, v119
	v_add_f32_e32 v161, v118, v119
	ds_bpermute_b32 v172, v248, v161
	v_cndmask_b32_e64 v114, v114, v115, s[66:67]
	v_cndmask_b32_e64 v114, v114, v116, s[40:41]
	v_cndmask_b32_e64 v114, v114, v117, s[68:69]
	s_waitcnt vmcnt(12)
	ds_write_b128 v244, v[42:45] offset:4096
	ds_write_b128 v245, v[34:37] offset:4096
	ds_write_b128 v246, v[38:41] offset:4096
	ds_write_b128 v247, v[46:49] offset:4096
	global_load_dwordx4 v[34:37], v[226:227], off offset:64
	global_load_dwordx4 v[38:41], v[226:227], off offset:128
	global_load_dwordx4 v[42:45], v[226:227], off
	global_load_dwordx4 v[46:49], v[226:227], off offset:192
	v_add_u32_e32 v0, v146, v147
	ds_read_b128 v[232:235], v0 offset:4096
	v_add_u32_e32 v0, v146, v148
	ds_read_b128 v[236:239], v0 offset:4096
	v_add_u32_e32 v0, v146, v149
	ds_read_b128 v[240:243], v0 offset:4096
	v_add_u32_e32 v0, v146, v150
	v_mov_b32_e32 v115, 0
	s_waitcnt lgkmcnt(2)
	v_dot2_f32_bf16 v115, v232, v232, v115
	v_dot2_f32_bf16 v115, v233, v233, v115
	v_dot2_f32_bf16 v115, v234, v234, v115
	v_dot2_f32_bf16 v115, v235, v235, v115
	v_mfma_f32_16x16x32_bf16 v[116:119], v[2:5], v[232:235], 0
	ds_read_b128 v[232:235], v0 offset:4096
	s_waitcnt lgkmcnt(2)
	v_dot2_f32_bf16 v115, v236, v236, v115
	v_dot2_f32_bf16 v115, v237, v237, v115
	v_dot2_f32_bf16 v115, v238, v238, v115
	v_dot2_f32_bf16 v115, v239, v239, v115
	v_mfma_f32_16x16x32_bf16 v[116:119], v[6:9], v[236:239], v[116:119]
	s_waitcnt lgkmcnt(1)
	v_dot2_f32_bf16 v115, v240, v240, v115
	v_dot2_f32_bf16 v115, v241, v241, v115
	v_dot2_f32_bf16 v115, v242, v242, v115
	v_dot2_f32_bf16 v115, v243, v243, v115
	v_mfma_f32_16x16x32_bf16 v[116:119], v[10:13], v[240:243], v[116:119]
	s_waitcnt lgkmcnt(0)
; #define LAS __attribute__((address_space(3)))
;     ...
;       for (int b = 0; b < nb; ++b) {
;           float lgv[4], rsv[4];
; #pragma unroll
;           for (int jj = 0; jj < 4; ++jj) {
;               const int rho = jj * 16 + c16, slot = b * 64 + rho;
;               f32x4 a = {0.f, 0.f, 0.f, 0.f}; float ss = 0.f;
; #pragma unroll
;               for (int ks = 0; ks < 4; ++ks) {
; #pragma unroll
;                   for (int e = 0; e < 4; ++e) asm("v_dot2_f32_bf16 %0, %1, %1, %0" : "+v"(ss) : "v"(w[jj][ks][e]));
;                   a = __builtin_amdgcn_mfma_f32_16x16x32_bf16(qa[ks], *reinterpret_cast<const bf16x8*>(&w[jj][ks]), a, 0, 0, 0);
;                   *(LAS u32x4*)(wbase + rho * 256 + (((ks * 4 + quad) ^ fsw) << 4)) = w[jj][ks]; }
;               ss += __shfl_xor(ss, 16); ss += __shfl_xor(ss, 32);
;               const float rstd = rsqrtf(ss * (1.f / 128.f) + EPS);
;               const float av = quad == 0 ? a[0] : (quad == 1 ? a[1] : (quad == 2 ? a[2] : a[3]));
;               rsv[jj] = rstd; lgv[jj] = (slot < kcount) ? av * rstd * 0.08838834764831845f : -__builtin_inff();
;           }
;           if (b + 1 < nb) gl(b + 1);
	v_dot2_f32_bf16 v115, v232, v232, v115
	v_dot2_f32_bf16 v115, v233, v233, v115
	v_dot2_f32_bf16 v115, v234, v234, v115
	v_dot2_f32_bf16 v115, v235, v235, v115
	v_mfma_f32_16x16x32_bf16 v[116:119], v[14:17], v[232:235], v[116:119]
	s_nop 2
	v_mov_b32_e32 v120, v115
	s_nop 1
	v_permlane16_swap_b32_e32 v115, v120
	v_add_f32_e32 v115, v115, v120
	ds_bpermute_b32 v173, v248, v115
	v_cndmask_b32_e64 v116, v116, v117, s[66:67]
	v_cndmask_b32_e64 v116, v116, v118, s[40:41]
	v_cndmask_b32_e64 v116, v116, v119, s[68:69]
	s_waitcnt vmcnt(12)
	ds_write_b128 v244, v[58:61] offset:8192
	ds_write_b128 v245, v[50:53] offset:8192
	ds_write_b128 v246, v[54:57] offset:8192
	ds_write_b128 v247, v[62:65] offset:8192
	global_load_dwordx4 v[50:53], v[228:229], off offset:64
	global_load_dwordx4 v[54:57], v[228:229], off offset:128
	global_load_dwordx4 v[58:61], v[228:229], off
	global_load_dwordx4 v[62:65], v[228:229], off offset:192
	v_add_u32_e32 v0, v146, v147
	ds_read_b128 v[232:235], v0 offset:8192
	v_add_u32_e32 v0, v146, v148
	ds_read_b128 v[236:239], v0 offset:8192
	v_add_u32_e32 v0, v146, v149
	ds_read_b128 v[240:243], v0 offset:8192
	v_add_u32_e32 v0, v146, v150
	v_mov_b32_e32 v117, 0
	s_waitcnt lgkmcnt(2)
	v_dot2_f32_bf16 v117, v232, v232, v117
	v_dot2_f32_bf16 v117, v233, v233, v117
	v_dot2_f32_bf16 v117, v234, v234, v117
	v_dot2_f32_bf16 v117, v235, v235, v117
	v_mfma_f32_16x16x32_bf16 v[118:121], v[2:5], v[232:235], 0
	ds_read_b128 v[232:235], v0 offset:8192
	s_waitcnt lgkmcnt(2)
	v_dot2_f32_bf16 v117, v236, v236, v117
	v_dot2_f32_bf16 v117, v237, v237, v117
	v_dot2_f32_bf16 v117, v238, v238, v117
	v_dot2_f32_bf16 v117, v239, v239, v117
	v_mfma_f32_16x16x32_bf16 v[118:121], v[6:9], v[236:239], v[118:121]
	s_waitcnt lgkmcnt(1)
	v_dot2_f32_bf16 v117, v240, v240, v117
	v_dot2_f32_bf16 v117, v241, v241, v117
	v_dot2_f32_bf16 v117, v242, v242, v117
	v_dot2_f32_bf16 v117, v243, v243, v117
	v_mfma_f32_16x16x32_bf16 v[118:121], v[10:13], v[240:243], v[118:121]
	s_waitcnt lgkmcnt(0)
	v_dot2_f32_bf16 v117, v232, v232, v117
	v_dot2_f32_bf16 v117, v233, v233, v117
	v_dot2_f32_bf16 v117, v234, v234, v117
	v_dot2_f32_bf16 v117, v235, v235, v117
	v_mfma_f32_16x16x32_bf16 v[118:121], v[14:17], v[232:235], v[118:121]
	s_nop 2
	v_mov_b32_e32 v123, v117
	s_nop 1
	v_permlane16_swap_b32_e32 v117, v123
	v_add_f32_e32 v117, v117, v123
	ds_bpermute_b32 v174, v248, v117
	v_cndmask_b32_e64 v118, v118, v119, s[66:67]
	v_cndmask_b32_e64 v118, v118, v120, s[40:41]
	v_cndmask_b32_e64 v118, v118, v121, s[68:69]
	s_waitcnt vmcnt(12)
	ds_write_b128 v244, v[74:77] offset:12288
	ds_write_b128 v245, v[66:69] offset:12288
	ds_write_b128 v246, v[70:73] offset:12288
	ds_write_b128 v247, v[78:81] offset:12288
	global_load_dwordx4 v[66:69], v[230:231], off offset:64
	global_load_dwordx4 v[70:73], v[230:231], off offset:128
	global_load_dwordx4 v[74:77], v[230:231], off
	global_load_dwordx4 v[78:81], v[230:231], off offset:192
	v_add_u32_e32 v0, v146, v147
	ds_read_b128 v[232:235], v0 offset:12288
	v_add_u32_e32 v0, v146, v148
	ds_read_b128 v[236:239], v0 offset:12288
	v_add_u32_e32 v0, v146, v149
	ds_read_b128 v[240:243], v0 offset:12288
	v_add_u32_e32 v0, v146, v150
	v_mov_b32_e32 v119, 0
	s_waitcnt lgkmcnt(2)
	v_dot2_f32_bf16 v119, v232, v232, v119
	v_dot2_f32_bf16 v119, v233, v233, v119
	v_dot2_f32_bf16 v119, v234, v234, v119
	v_dot2_f32_bf16 v119, v235, v235, v119
	v_mfma_f32_16x16x32_bf16 v[176:179], v[2:5], v[232:235], 0
	ds_read_b128 v[232:235], v0 offset:12288
	s_waitcnt lgkmcnt(2)
	v_dot2_f32_bf16 v119, v236, v236, v119
	v_dot2_f32_bf16 v119, v237, v237, v119
	v_dot2_f32_bf16 v119, v238, v238, v119
	v_dot2_f32_bf16 v119, v239, v239, v119
	v_mfma_f32_16x16x32_bf16 v[176:179], v[6:9], v[236:239], v[176:179]
	s_waitcnt lgkmcnt(1)
	v_dot2_f32_bf16 v119, v240, v240, v119
	v_dot2_f32_bf16 v119, v241, v241, v119
	v_dot2_f32_bf16 v119, v242, v242, v119
	v_dot2_f32_bf16 v119, v243, v243, v119
	v_mfma_f32_16x16x32_bf16 v[176:179], v[10:13], v[240:243], v[176:179]
	s_waitcnt lgkmcnt(0)
	v_dot2_f32_bf16 v119, v232, v232, v119
	v_dot2_f32_bf16 v119, v233, v233, v119
	v_dot2_f32_bf16 v119, v234, v234, v119
	v_dot2_f32_bf16 v119, v235, v235, v119
	v_mfma_f32_16x16x32_bf16 v[120:123], v[14:17], v[232:235], v[176:179]
	s_nop 2
	v_mov_b32_e32 v0, v119
	s_nop 1
	v_permlane16_swap_b32_e32 v119, v0
	v_add_f32_e32 v119, v119, v0
	ds_bpermute_b32 v175, v248, v119
	v_cndmask_b32_e64 v120, v120, v121, s[66:67]
	v_cndmask_b32_e64 v120, v120, v122, s[40:41]
	v_cndmask_b32_e64 v120, v120, v123, s[68:69]
	s_add_i32 s24, s24, 1
	s_branch .LBB0_946
